# D epilogue v5: packed f32 (v_pk_mul/v_pk_fma) for scale, conv center tap, sigmoid denominator and output products
# speedup vs baseline: 1.0022x; 1.0022x over previous
.Ldepi_rs_cached:
	v_rcp_f32_e32 v170, v244
	v_rcp_f32_e32 v171, v245
	v_rcp_f32_e32 v172, v246
	v_rcp_f32_e32 v173, v247
	v_rcp_f32_e32 v169, v248
	v_rcp_f32_e32 v177, v249
	v_rcp_f32_e32 v191, v250
	v_rcp_f32_e32 v199, v251
	v_mul_f32_e32 v170, s101, v170
	v_mul_f32_e32 v171, s101, v171
	v_mul_f32_e32 v172, s101, v172
	v_mul_f32_e32 v173, s101, v173
	v_mul_f32_e32 v169, s101, v169
	v_mul_f32_e32 v177, s101, v177
	v_mul_f32_e32 v191, s101, v191
	v_mul_f32_e32 v199, s101, v199
	v_pk_mul_f32 v[146:147], v[146:147], v[244:245] op_sel:[0,0] op_sel_hi:[1,0]
	v_pk_mul_f32 v[158:159], v[158:159], v[244:245] op_sel:[0,1] op_sel_hi:[1,1]
	v_pk_mul_f32 v[154:155], v[154:155], v[246:247] op_sel:[0,0] op_sel_hi:[1,0]
	v_pk_mul_f32 v[150:151], v[150:151], v[246:247] op_sel:[0,1] op_sel_hi:[1,1]
	v_pk_mul_f32 v[148:149], v[148:149], v[244:245] op_sel:[0,0] op_sel_hi:[1,0]
	v_pk_mul_f32 v[160:161], v[160:161], v[244:245] op_sel:[0,1] op_sel_hi:[1,1]
	v_pk_mul_f32 v[156:157], v[156:157], v[246:247] op_sel:[0,0] op_sel_hi:[1,0]
	v_pk_mul_f32 v[152:153], v[152:153], v[246:247] op_sel:[0,1] op_sel_hi:[1,1]
	v_pk_mul_f32 v[116:117], v[116:117], v[244:245] op_sel:[0,0] op_sel_hi:[1,0]
	v_pk_mul_f32 v[124:125], v[124:125], v[244:245] op_sel:[0,1] op_sel_hi:[1,1]
	v_pk_mul_f32 v[112:113], v[112:113], v[246:247] op_sel:[0,0] op_sel_hi:[1,0]
	v_pk_mul_f32 v[120:121], v[120:121], v[246:247] op_sel:[0,1] op_sel_hi:[1,1]
	v_pk_mul_f32 v[118:119], v[118:119], v[244:245] op_sel:[0,0] op_sel_hi:[1,0]
	v_pk_mul_f32 v[126:127], v[126:127], v[244:245] op_sel:[0,1] op_sel_hi:[1,1]
	v_pk_mul_f32 v[114:115], v[114:115], v[246:247] op_sel:[0,0] op_sel_hi:[1,0]
	v_pk_mul_f32 v[122:123], v[122:123], v[246:247] op_sel:[0,1] op_sel_hi:[1,1]
	v_pk_mul_f32 v[48:49], v[48:49], v[248:249] op_sel:[0,0] op_sel_hi:[1,0]
	v_pk_mul_f32 v[60:61], v[60:61], v[248:249] op_sel:[0,1] op_sel_hi:[1,1]
	v_pk_mul_f32 v[56:57], v[56:57], v[250:251] op_sel:[0,0] op_sel_hi:[1,0]
	v_pk_mul_f32 v[52:53], v[52:53], v[250:251] op_sel:[0,1] op_sel_hi:[1,1]
	v_pk_mul_f32 v[50:51], v[50:51], v[248:249] op_sel:[0,0] op_sel_hi:[1,0]
	v_pk_mul_f32 v[62:63], v[62:63], v[248:249] op_sel:[0,1] op_sel_hi:[1,1]
	v_pk_mul_f32 v[58:59], v[58:59], v[250:251] op_sel:[0,0] op_sel_hi:[1,0]
	v_pk_mul_f32 v[54:55], v[54:55], v[250:251] op_sel:[0,1] op_sel_hi:[1,1]
	v_pk_mul_f32 v[20:21], v[20:21], v[248:249] op_sel:[0,0] op_sel_hi:[1,0]
	v_pk_mul_f32 v[28:29], v[28:29], v[248:249] op_sel:[0,1] op_sel_hi:[1,1]
	v_pk_mul_f32 v[16:17], v[16:17], v[250:251] op_sel:[0,0] op_sel_hi:[1,0]
	v_pk_mul_f32 v[24:25], v[24:25], v[250:251] op_sel:[0,1] op_sel_hi:[1,1]
	v_pk_mul_f32 v[22:23], v[22:23], v[248:249] op_sel:[0,0] op_sel_hi:[1,0]
	v_pk_mul_f32 v[30:31], v[30:31], v[248:249] op_sel:[0,1] op_sel_hi:[1,1]
	v_pk_mul_f32 v[18:19], v[18:19], v[250:251] op_sel:[0,0] op_sel_hi:[1,0]
	v_pk_mul_f32 v[26:27], v[26:27], v[250:251] op_sel:[0,1] op_sel_hi:[1,1]
	s_waitcnt vmcnt(0)
	v_pk_mul_f32 v[64:65], v[64:65], s[100:101] op_sel:[0,1] op_sel_hi:[1,1]
	v_pk_mul_f32 v[66:67], v[66:67], s[100:101] op_sel:[0,1] op_sel_hi:[1,1]
	v_pk_mul_f32 v[68:69], v[68:69], s[100:101] op_sel:[0,1] op_sel_hi:[1,1]
	v_pk_mul_f32 v[70:71], v[70:71], s[100:101] op_sel:[0,1] op_sel_hi:[1,1]
	v_pk_mul_f32 v[72:73], v[72:73], s[100:101] op_sel:[0,1] op_sel_hi:[1,1]
	v_pk_mul_f32 v[74:75], v[74:75], s[100:101] op_sel:[0,1] op_sel_hi:[1,1]
	v_pk_mul_f32 v[76:77], v[76:77], s[100:101] op_sel:[0,1] op_sel_hi:[1,1]
	v_pk_mul_f32 v[78:79], v[78:79], s[100:101] op_sel:[0,1] op_sel_hi:[1,1]
	v_pk_mul_f32 v[80:81], v[80:81], s[100:101] op_sel:[0,1] op_sel_hi:[1,1]
	v_pk_mul_f32 v[82:83], v[82:83], s[100:101] op_sel:[0,1] op_sel_hi:[1,1]
	v_pk_mul_f32 v[84:85], v[84:85], s[100:101] op_sel:[0,1] op_sel_hi:[1,1]
	v_pk_mul_f32 v[86:87], v[86:87], s[100:101] op_sel:[0,1] op_sel_hi:[1,1]
	v_pk_mul_f32 v[88:89], v[88:89], s[100:101] op_sel:[0,1] op_sel_hi:[1,1]
	v_pk_mul_f32 v[90:91], v[90:91], s[100:101] op_sel:[0,1] op_sel_hi:[1,1]
	v_pk_mul_f32 v[92:93], v[92:93], s[100:101] op_sel:[0,1] op_sel_hi:[1,1]
	v_pk_mul_f32 v[94:95], v[94:95], s[100:101] op_sel:[0,1] op_sel_hi:[1,1]
	v_cndmask_b32_e64 v222, v146, 0, s[36:37]
	v_cndmask_b32_e64 v236, v146, 0, s[44:45]
	v_cndmask_b32_e64 v224, v158, v146, s[36:37]
	v_cndmask_b32_e64 v237, v158, v146, s[44:45]
	v_cndmask_b32_e64 v226, v154, v158, s[36:37]
	v_cndmask_b32_e64 v238, v154, v158, s[44:45]
	v_cndmask_b32_e64 v228, v150, v154, s[36:37]
	v_cndmask_b32_e64 v239, v150, v154, s[44:45]
	v_cndmask_b32_e64 v223, v147, 0, s[36:37]
	v_cndmask_b32_e64 v196, v147, 0, s[44:45]
	v_cndmask_b32_e64 v225, v159, v147, s[36:37]
	v_cndmask_b32_e64 v197, v159, v147, s[44:45]
	v_cndmask_b32_e64 v227, v155, v159, s[36:37]
	v_cndmask_b32_e64 v221, v155, v159, s[44:45]
	v_cndmask_b32_e64 v229, v151, v155, s[36:37]
	v_cndmask_b32_e64 v176, v151, v155, s[44:45]
	v_pk_fma_f32 v[200:201], v[92:93], v[146:147], v[84:85]
	v_pk_fma_f32 v[230:231], v[92:93], v[158:159], v[84:85]
	v_pk_fma_f32 v[232:233], v[92:93], v[154:155], v[84:85]
	v_pk_fma_f32 v[234:235], v[92:93], v[150:151], v[84:85]
	v_fmac_f32_dpp v200, v222, v88 row_ror:1 row_mask:0xf bank_mask:0xf
	v_fmac_f32_dpp v230, v224, v88 row_ror:1 row_mask:0xf bank_mask:0xf
	v_fmac_f32_dpp v232, v226, v88 row_ror:1 row_mask:0xf bank_mask:0xf
	v_fmac_f32_dpp v234, v228, v88 row_ror:1 row_mask:0xf bank_mask:0xf
	v_fmac_f32_dpp v201, v223, v89 row_ror:1 row_mask:0xf bank_mask:0xf
	v_fmac_f32_dpp v231, v225, v89 row_ror:1 row_mask:0xf bank_mask:0xf
	v_fmac_f32_dpp v233, v227, v89 row_ror:1 row_mask:0xf bank_mask:0xf
	v_fmac_f32_dpp v235, v229, v89 row_ror:1 row_mask:0xf bank_mask:0xf
	v_fmac_f32_dpp v200, v236, v80 row_ror:2 row_mask:0xf bank_mask:0xf
	v_fmac_f32_dpp v230, v237, v80 row_ror:2 row_mask:0xf bank_mask:0xf
	v_fmac_f32_dpp v232, v238, v80 row_ror:2 row_mask:0xf bank_mask:0xf
	v_fmac_f32_dpp v234, v239, v80 row_ror:2 row_mask:0xf bank_mask:0xf
	v_fmac_f32_dpp v201, v196, v81 row_ror:2 row_mask:0xf bank_mask:0xf
	v_fmac_f32_dpp v231, v197, v81 row_ror:2 row_mask:0xf bank_mask:0xf
	v_fmac_f32_dpp v233, v221, v81 row_ror:2 row_mask:0xf bank_mask:0xf
	v_fmac_f32_dpp v235, v176, v81 row_ror:2 row_mask:0xf bank_mask:0xf
	v_exp_f32_e32 v222, v200
	v_exp_f32_e32 v224, v230
	v_exp_f32_e32 v226, v232
	v_exp_f32_e32 v228, v234
	v_exp_f32_e32 v223, v201
	v_exp_f32_e32 v225, v231
	v_exp_f32_e32 v227, v233
	v_exp_f32_e32 v229, v235
	v_pk_fma_f32 v[222:223], v[222:223], v[170:171], v[170:171] op_sel:[0,0,0] op_sel_hi:[1,0,0]
	v_pk_fma_f32 v[224:225], v[224:225], v[170:171], v[170:171] op_sel:[0,1,1] op_sel_hi:[1,1,1]
	v_pk_fma_f32 v[226:227], v[226:227], v[172:173], v[172:173] op_sel:[0,0,0] op_sel_hi:[1,0,0]
	v_pk_fma_f32 v[228:229], v[228:229], v[172:173], v[172:173] op_sel:[0,1,1] op_sel_hi:[1,1,1]
	v_rcp_f32_e32 v222, v222
	v_rcp_f32_e32 v224, v224
	v_rcp_f32_e32 v226, v226
	v_rcp_f32_e32 v228, v228
	v_rcp_f32_e32 v223, v223
	v_rcp_f32_e32 v225, v225
	v_rcp_f32_e32 v227, v227
	v_rcp_f32_e32 v229, v229
	v_pk_mul_f32 v[222:223], v[200:201], v[222:223]
	v_pk_mul_f32 v[224:225], v[230:231], v[224:225]
	v_pk_mul_f32 v[226:227], v[232:233], v[226:227]
	v_pk_mul_f32 v[228:229], v[234:235], v[228:229]
	v_pk_mul_f32 v[192:193], v[140:141], v[244:245] op_sel:[0,0] op_sel_hi:[1,0]
	v_pk_mul_f32 v[140:141], v[222:223], v[140:141]
	v_pk_mul_f32 v[136:137], v[224:225], v[136:137]
	v_pk_mul_f32 v[132:133], v[226:227], v[132:133]
	v_pk_mul_f32 v[128:129], v[228:229], v[128:129]
	v_cndmask_b32_e64 v222, v148, 0, s[36:37]
	v_cndmask_b32_e64 v236, v148, 0, s[44:45]
	v_cndmask_b32_e64 v224, v160, v148, s[36:37]
	v_cndmask_b32_e64 v237, v160, v148, s[44:45]
	v_cndmask_b32_e64 v226, v156, v160, s[36:37]
	v_cndmask_b32_e64 v238, v156, v160, s[44:45]
	v_cndmask_b32_e64 v228, v152, v156, s[36:37]
	v_cndmask_b32_e64 v239, v152, v156, s[44:45]
	v_cndmask_b32_e64 v223, v149, 0, s[36:37]
	v_cndmask_b32_e64 v196, v149, 0, s[44:45]
	v_cndmask_b32_e64 v225, v161, v149, s[36:37]
	v_cndmask_b32_e64 v197, v161, v149, s[44:45]
	v_cndmask_b32_e64 v227, v157, v161, s[36:37]
	v_cndmask_b32_e64 v221, v157, v161, s[44:45]
	v_cndmask_b32_e64 v229, v153, v157, s[36:37]
	v_cndmask_b32_e64 v176, v153, v157, s[44:45]
	v_pk_fma_f32 v[202:203], v[94:95], v[148:149], v[86:87]
	v_pk_fma_f32 v[230:231], v[94:95], v[160:161], v[86:87]
	v_pk_fma_f32 v[232:233], v[94:95], v[156:157], v[86:87]
	v_pk_fma_f32 v[234:235], v[94:95], v[152:153], v[86:87]
	v_fmac_f32_dpp v202, v222, v90 row_ror:1 row_mask:0xf bank_mask:0xf
	v_fmac_f32_dpp v230, v224, v90 row_ror:1 row_mask:0xf bank_mask:0xf
	v_fmac_f32_dpp v232, v226, v90 row_ror:1 row_mask:0xf bank_mask:0xf
	v_fmac_f32_dpp v234, v228, v90 row_ror:1 row_mask:0xf bank_mask:0xf
	v_fmac_f32_dpp v203, v223, v91 row_ror:1 row_mask:0xf bank_mask:0xf
	v_fmac_f32_dpp v231, v225, v91 row_ror:1 row_mask:0xf bank_mask:0xf
	v_fmac_f32_dpp v233, v227, v91 row_ror:1 row_mask:0xf bank_mask:0xf
	v_fmac_f32_dpp v235, v229, v91 row_ror:1 row_mask:0xf bank_mask:0xf
	v_fmac_f32_dpp v202, v236, v82 row_ror:2 row_mask:0xf bank_mask:0xf
	v_fmac_f32_dpp v230, v237, v82 row_ror:2 row_mask:0xf bank_mask:0xf
	v_fmac_f32_dpp v232, v238, v82 row_ror:2 row_mask:0xf bank_mask:0xf
	v_fmac_f32_dpp v234, v239, v82 row_ror:2 row_mask:0xf bank_mask:0xf
	v_fmac_f32_dpp v203, v196, v83 row_ror:2 row_mask:0xf bank_mask:0xf
	v_fmac_f32_dpp v231, v197, v83 row_ror:2 row_mask:0xf bank_mask:0xf
	v_fmac_f32_dpp v233, v221, v83 row_ror:2 row_mask:0xf bank_mask:0xf
	v_fmac_f32_dpp v235, v176, v83 row_ror:2 row_mask:0xf bank_mask:0xf
	v_exp_f32_e32 v222, v202
	v_exp_f32_e32 v224, v230
	v_exp_f32_e32 v226, v232
	v_exp_f32_e32 v228, v234
	v_exp_f32_e32 v223, v203
	v_exp_f32_e32 v225, v231
	v_exp_f32_e32 v227, v233
	v_exp_f32_e32 v229, v235
	v_pk_fma_f32 v[222:223], v[222:223], v[170:171], v[170:171] op_sel:[0,0,0] op_sel_hi:[1,0,0]
	v_pk_fma_f32 v[224:225], v[224:225], v[170:171], v[170:171] op_sel:[0,1,1] op_sel_hi:[1,1,1]
	v_pk_fma_f32 v[226:227], v[226:227], v[172:173], v[172:173] op_sel:[0,0,0] op_sel_hi:[1,0,0]
	v_pk_fma_f32 v[228:229], v[228:229], v[172:173], v[172:173] op_sel:[0,1,1] op_sel_hi:[1,1,1]
	v_rcp_f32_e32 v222, v222
	v_rcp_f32_e32 v224, v224
	v_rcp_f32_e32 v226, v226
	v_rcp_f32_e32 v228, v228
	v_rcp_f32_e32 v223, v223
	v_rcp_f32_e32 v225, v225
	v_rcp_f32_e32 v227, v227
	v_rcp_f32_e32 v229, v229
	v_pk_mul_f32 v[222:223], v[202:203], v[222:223]
	v_pk_mul_f32 v[224:225], v[230:231], v[224:225]
	v_pk_mul_f32 v[226:227], v[232:233], v[226:227]
	v_pk_mul_f32 v[228:229], v[234:235], v[228:229]
	v_pk_mul_f32 v[194:195], v[142:143], v[244:245] op_sel:[0,0] op_sel_hi:[1,0]
	v_pk_mul_f32 v[142:143], v[222:223], v[142:143]
	v_pk_mul_f32 v[138:139], v[224:225], v[138:139]
	v_pk_mul_f32 v[134:135], v[226:227], v[134:135]
	v_pk_mul_f32 v[130:131], v[228:229], v[130:131]
	v_cndmask_b32_e64 v222, v116, 0, s[36:37]
	v_cndmask_b32_e64 v236, v116, 0, s[44:45]
	v_cndmask_b32_e64 v224, v124, v116, s[36:37]
	v_cndmask_b32_e64 v237, v124, v116, s[44:45]
	v_cndmask_b32_e64 v226, v112, v124, s[36:37]
	v_cndmask_b32_e64 v238, v112, v124, s[44:45]
	v_cndmask_b32_e64 v228, v120, v112, s[36:37]
	v_cndmask_b32_e64 v239, v120, v112, s[44:45]
	v_cndmask_b32_e64 v223, v117, 0, s[36:37]
	v_cndmask_b32_e64 v196, v117, 0, s[44:45]
	v_cndmask_b32_e64 v225, v125, v117, s[36:37]
	v_cndmask_b32_e64 v197, v125, v117, s[44:45]
	v_cndmask_b32_e64 v227, v113, v125, s[36:37]
	v_cndmask_b32_e64 v221, v113, v125, s[44:45]
	v_cndmask_b32_e64 v229, v121, v113, s[36:37]
	v_cndmask_b32_e64 v176, v121, v113, s[44:45]
	v_pk_fma_f32 v[204:205], v[76:77], v[116:117], v[68:69]
	v_pk_fma_f32 v[230:231], v[76:77], v[124:125], v[68:69]
	v_pk_fma_f32 v[232:233], v[76:77], v[112:113], v[68:69]
	v_pk_fma_f32 v[234:235], v[76:77], v[120:121], v[68:69]
	v_fmac_f32_dpp v204, v222, v72 row_ror:1 row_mask:0xf bank_mask:0xf
	v_fmac_f32_dpp v230, v224, v72 row_ror:1 row_mask:0xf bank_mask:0xf
	v_fmac_f32_dpp v232, v226, v72 row_ror:1 row_mask:0xf bank_mask:0xf
	v_fmac_f32_dpp v234, v228, v72 row_ror:1 row_mask:0xf bank_mask:0xf
	v_fmac_f32_dpp v205, v223, v73 row_ror:1 row_mask:0xf bank_mask:0xf
	v_fmac_f32_dpp v231, v225, v73 row_ror:1 row_mask:0xf bank_mask:0xf
	v_fmac_f32_dpp v233, v227, v73 row_ror:1 row_mask:0xf bank_mask:0xf
	v_fmac_f32_dpp v235, v229, v73 row_ror:1 row_mask:0xf bank_mask:0xf
	v_fmac_f32_dpp v204, v236, v64 row_ror:2 row_mask:0xf bank_mask:0xf
	v_fmac_f32_dpp v230, v237, v64 row_ror:2 row_mask:0xf bank_mask:0xf
	v_fmac_f32_dpp v232, v238, v64 row_ror:2 row_mask:0xf bank_mask:0xf
	v_fmac_f32_dpp v234, v239, v64 row_ror:2 row_mask:0xf bank_mask:0xf
	v_fmac_f32_dpp v205, v196, v65 row_ror:2 row_mask:0xf bank_mask:0xf
	v_fmac_f32_dpp v231, v197, v65 row_ror:2 row_mask:0xf bank_mask:0xf
	v_fmac_f32_dpp v233, v221, v65 row_ror:2 row_mask:0xf bank_mask:0xf
	v_fmac_f32_dpp v235, v176, v65 row_ror:2 row_mask:0xf bank_mask:0xf
	v_exp_f32_e32 v222, v204
	v_exp_f32_e32 v224, v230
	v_exp_f32_e32 v226, v232
	v_exp_f32_e32 v228, v234
	v_exp_f32_e32 v223, v205
	v_exp_f32_e32 v225, v231
	v_exp_f32_e32 v227, v233
	v_exp_f32_e32 v229, v235
	v_pk_fma_f32 v[222:223], v[222:223], v[170:171], v[170:171] op_sel:[0,0,0] op_sel_hi:[1,0,0]
	v_pk_fma_f32 v[224:225], v[224:225], v[170:171], v[170:171] op_sel:[0,1,1] op_sel_hi:[1,1,1]
	v_pk_fma_f32 v[226:227], v[226:227], v[172:173], v[172:173] op_sel:[0,0,0] op_sel_hi:[1,0,0]
	v_pk_fma_f32 v[228:229], v[228:229], v[172:173], v[172:173] op_sel:[0,1,1] op_sel_hi:[1,1,1]
	v_rcp_f32_e32 v222, v222
	v_rcp_f32_e32 v224, v224
	v_rcp_f32_e32 v226, v226
	v_rcp_f32_e32 v228, v228
	v_rcp_f32_e32 v223, v223
	v_rcp_f32_e32 v225, v225
	v_rcp_f32_e32 v227, v227
	v_rcp_f32_e32 v229, v229
	v_pk_mul_f32 v[222:223], v[204:205], v[222:223]
	v_pk_mul_f32 v[224:225], v[230:231], v[224:225]
	v_pk_mul_f32 v[226:227], v[232:233], v[226:227]
	v_pk_mul_f32 v[228:229], v[234:235], v[228:229]
	v_pk_mul_f32 v[240:241], v[108:109], v[244:245] op_sel:[0,0] op_sel_hi:[1,0]
	v_pk_mul_f32 v[108:109], v[222:223], v[108:109]
	v_pk_mul_f32 v[104:105], v[224:225], v[104:105]
	v_pk_mul_f32 v[100:101], v[226:227], v[100:101]
	v_pk_mul_f32 v[96:97], v[228:229], v[96:97]
	v_cndmask_b32_e64 v222, v118, 0, s[36:37]
	v_cndmask_b32_e64 v236, v118, 0, s[44:45]
	v_cndmask_b32_e64 v224, v126, v118, s[36:37]
	v_cndmask_b32_e64 v237, v126, v118, s[44:45]
	v_cndmask_b32_e64 v226, v114, v126, s[36:37]
	v_cndmask_b32_e64 v238, v114, v126, s[44:45]
	v_cndmask_b32_e64 v228, v122, v114, s[36:37]
	v_cndmask_b32_e64 v239, v122, v114, s[44:45]
	v_cndmask_b32_e64 v223, v119, 0, s[36:37]
	v_cndmask_b32_e64 v196, v119, 0, s[44:45]
	v_cndmask_b32_e64 v225, v127, v119, s[36:37]
	v_cndmask_b32_e64 v197, v127, v119, s[44:45]
	v_cndmask_b32_e64 v227, v115, v127, s[36:37]
	v_cndmask_b32_e64 v221, v115, v127, s[44:45]
	v_cndmask_b32_e64 v229, v123, v115, s[36:37]
	v_cndmask_b32_e64 v176, v123, v115, s[44:45]
	v_pk_fma_f32 v[206:207], v[78:79], v[118:119], v[70:71]
	v_pk_fma_f32 v[230:231], v[78:79], v[126:127], v[70:71]
	v_pk_fma_f32 v[232:233], v[78:79], v[114:115], v[70:71]
	v_pk_fma_f32 v[234:235], v[78:79], v[122:123], v[70:71]
	v_fmac_f32_dpp v206, v222, v74 row_ror:1 row_mask:0xf bank_mask:0xf
	v_fmac_f32_dpp v230, v224, v74 row_ror:1 row_mask:0xf bank_mask:0xf
	v_fmac_f32_dpp v232, v226, v74 row_ror:1 row_mask:0xf bank_mask:0xf
	v_fmac_f32_dpp v234, v228, v74 row_ror:1 row_mask:0xf bank_mask:0xf
	v_fmac_f32_dpp v207, v223, v75 row_ror:1 row_mask:0xf bank_mask:0xf
	v_fmac_f32_dpp v231, v225, v75 row_ror:1 row_mask:0xf bank_mask:0xf
	v_fmac_f32_dpp v233, v227, v75 row_ror:1 row_mask:0xf bank_mask:0xf
	v_fmac_f32_dpp v235, v229, v75 row_ror:1 row_mask:0xf bank_mask:0xf
	v_fmac_f32_dpp v206, v236, v66 row_ror:2 row_mask:0xf bank_mask:0xf
	v_fmac_f32_dpp v230, v237, v66 row_ror:2 row_mask:0xf bank_mask:0xf
	v_fmac_f32_dpp v232, v238, v66 row_ror:2 row_mask:0xf bank_mask:0xf
	v_fmac_f32_dpp v234, v239, v66 row_ror:2 row_mask:0xf bank_mask:0xf
	v_fmac_f32_dpp v207, v196, v67 row_ror:2 row_mask:0xf bank_mask:0xf
	v_fmac_f32_dpp v231, v197, v67 row_ror:2 row_mask:0xf bank_mask:0xf
	v_fmac_f32_dpp v233, v221, v67 row_ror:2 row_mask:0xf bank_mask:0xf
	v_fmac_f32_dpp v235, v176, v67 row_ror:2 row_mask:0xf bank_mask:0xf
	v_exp_f32_e32 v222, v206
	v_exp_f32_e32 v224, v230
	v_exp_f32_e32 v226, v232
	v_exp_f32_e32 v228, v234
	v_exp_f32_e32 v223, v207
	v_exp_f32_e32 v225, v231
	v_exp_f32_e32 v227, v233
	v_exp_f32_e32 v229, v235
	v_pk_fma_f32 v[222:223], v[222:223], v[170:171], v[170:171] op_sel:[0,0,0] op_sel_hi:[1,0,0]
	v_pk_fma_f32 v[224:225], v[224:225], v[170:171], v[170:171] op_sel:[0,1,1] op_sel_hi:[1,1,1]
	v_pk_fma_f32 v[226:227], v[226:227], v[172:173], v[172:173] op_sel:[0,0,0] op_sel_hi:[1,0,0]
	v_pk_fma_f32 v[228:229], v[228:229], v[172:173], v[172:173] op_sel:[0,1,1] op_sel_hi:[1,1,1]
	v_rcp_f32_e32 v222, v222
	v_rcp_f32_e32 v224, v224
	v_rcp_f32_e32 v226, v226
	v_rcp_f32_e32 v228, v228
	v_rcp_f32_e32 v223, v223
	v_rcp_f32_e32 v225, v225
	v_rcp_f32_e32 v227, v227
	v_rcp_f32_e32 v229, v229
	v_pk_mul_f32 v[222:223], v[206:207], v[222:223]
	v_pk_mul_f32 v[224:225], v[230:231], v[224:225]
	v_pk_mul_f32 v[226:227], v[232:233], v[226:227]
	v_pk_mul_f32 v[228:229], v[234:235], v[228:229]
	v_pk_mul_f32 v[242:243], v[110:111], v[244:245] op_sel:[0,0] op_sel_hi:[1,0]
	v_pk_mul_f32 v[110:111], v[222:223], v[110:111]
	v_pk_mul_f32 v[106:107], v[224:225], v[106:107]
	v_pk_mul_f32 v[102:103], v[226:227], v[102:103]
	v_pk_mul_f32 v[98:99], v[228:229], v[98:99]
	v_cvt_pk_bf16_f32 v140, v140, v141
	v_cvt_pk_bf16_f32 v141, v142, v143
	v_cvt_pk_bf16_f32 v142, v108, v109
	v_cvt_pk_bf16_f32 v143, v110, v111
	v_cvt_pk_bf16_f32 v136, v136, v137
	v_cvt_pk_bf16_f32 v137, v138, v139
	v_cvt_pk_bf16_f32 v138, v104, v105
	v_cvt_pk_bf16_f32 v139, v106, v107
	v_cvt_pk_bf16_f32 v132, v132, v133
	v_cvt_pk_bf16_f32 v133, v134, v135
	v_cvt_pk_bf16_f32 v134, v100, v101
	v_cvt_pk_bf16_f32 v135, v102, v103
	v_cvt_pk_bf16_f32 v128, v128, v129
	v_cvt_pk_bf16_f32 v129, v130, v131
	v_cvt_pk_bf16_f32 v130, v96, v97
	v_cvt_pk_bf16_f32 v131, v98, v99
	v_mul_f32_e32 v200, 0xbf317218, v200
	v_mul_f32_e32 v201, 0xbf317218, v201
	v_mul_f32_e32 v202, 0xbf317218, v202
	v_mul_f32_e32 v203, 0xbf317218, v203
	v_mul_f32_e32 v204, 0xbf317218, v204
	v_mul_f32_e32 v205, 0xbf317218, v205
	v_mul_f32_e32 v206, 0xbf317218, v206
	v_mul_f32_e32 v207, 0xbf317218, v207
	v_or_b32_e32 v170, s11, v216
	v_mul_u32_u24_e32 v170, s10, v170
	v_lshl_add_u32 v170, v170, 2, v190
	s_and_saveexec_b64 s[0:1], s[42:43]
	global_store_dwordx4 v170, v[200:203], s[50:51]
	global_store_dwordx4 v170, v[204:207], s[50:51] offset:16
	global_store_dwordx4 v170, v[192:195], s[92:93]
	global_store_dwordx4 v170, v[240:243], s[92:93] offset:16
	s_or_b64 exec, exec, s[0:1]
	v_add_u32_e32 v171, s11, v218
	v_mul_u32_u24_e32 v171, s10, v171
	v_lshl_add_u32 v171, v171, 2, v190
	s_and_saveexec_b64 s[0:1], s[44:45]
	global_store_dwordx4 v171, v[150:153], s[52:53]
	global_store_dwordx4 v171, v[120:123], s[52:53] offset:16
	s_or_b64 exec, exec, s[0:1]
	v_mad_u32_u24 v172, v198, s20, v189
	s_and_saveexec_b64 s[0:1], s[40:41]
	global_store_dwordx4 v172, v[140:143], s[94:95]
	s_or_b64 exec, exec, s[0:1]
	v_add_u32_e32 v172, 0x16000, v172
	global_store_dwordx4 v172, v[136:139], s[94:95]
	v_add_u32_e32 v172, 0x16000, v172
	global_store_dwordx4 v172, v[132:135], s[94:95]
	v_add_u32_e32 v172, 0x16000, v172
	global_store_dwordx4 v172, v[128:131], s[94:95]
	s_add_i32 s11, s11, 4
	v_cndmask_b32_e64 v222, v48, 0, s[36:37]
	v_cndmask_b32_e64 v236, v48, 0, s[44:45]
	v_cndmask_b32_e64 v224, v60, v48, s[36:37]
	v_cndmask_b32_e64 v237, v60, v48, s[44:45]
	v_cndmask_b32_e64 v226, v56, v60, s[36:37]
	v_cndmask_b32_e64 v238, v56, v60, s[44:45]
	v_cndmask_b32_e64 v228, v52, v56, s[36:37]
	v_cndmask_b32_e64 v239, v52, v56, s[44:45]
	v_cndmask_b32_e64 v223, v49, 0, s[36:37]
	v_cndmask_b32_e64 v196, v49, 0, s[44:45]
	v_cndmask_b32_e64 v225, v61, v49, s[36:37]
	v_cndmask_b32_e64 v197, v61, v49, s[44:45]
	v_cndmask_b32_e64 v227, v57, v61, s[36:37]
	v_cndmask_b32_e64 v221, v57, v61, s[44:45]
	v_cndmask_b32_e64 v229, v53, v57, s[36:37]
	v_cndmask_b32_e64 v176, v53, v57, s[44:45]
	v_pk_fma_f32 v[200:201], v[92:93], v[48:49], v[84:85]
	v_pk_fma_f32 v[230:231], v[92:93], v[60:61], v[84:85]
	v_pk_fma_f32 v[232:233], v[92:93], v[56:57], v[84:85]
	v_pk_fma_f32 v[234:235], v[92:93], v[52:53], v[84:85]
	v_fmac_f32_dpp v200, v222, v88 row_ror:1 row_mask:0xf bank_mask:0xf
	v_fmac_f32_dpp v230, v224, v88 row_ror:1 row_mask:0xf bank_mask:0xf
	v_fmac_f32_dpp v232, v226, v88 row_ror:1 row_mask:0xf bank_mask:0xf
	v_fmac_f32_dpp v234, v228, v88 row_ror:1 row_mask:0xf bank_mask:0xf
	v_fmac_f32_dpp v201, v223, v89 row_ror:1 row_mask:0xf bank_mask:0xf
	v_fmac_f32_dpp v231, v225, v89 row_ror:1 row_mask:0xf bank_mask:0xf
	v_fmac_f32_dpp v233, v227, v89 row_ror:1 row_mask:0xf bank_mask:0xf
	v_fmac_f32_dpp v235, v229, v89 row_ror:1 row_mask:0xf bank_mask:0xf
	v_fmac_f32_dpp v200, v236, v80 row_ror:2 row_mask:0xf bank_mask:0xf
	v_fmac_f32_dpp v230, v237, v80 row_ror:2 row_mask:0xf bank_mask:0xf
	v_fmac_f32_dpp v232, v238, v80 row_ror:2 row_mask:0xf bank_mask:0xf
	v_fmac_f32_dpp v234, v239, v80 row_ror:2 row_mask:0xf bank_mask:0xf
	v_fmac_f32_dpp v201, v196, v81 row_ror:2 row_mask:0xf bank_mask:0xf
	v_fmac_f32_dpp v231, v197, v81 row_ror:2 row_mask:0xf bank_mask:0xf
	v_fmac_f32_dpp v233, v221, v81 row_ror:2 row_mask:0xf bank_mask:0xf
	v_fmac_f32_dpp v235, v176, v81 row_ror:2 row_mask:0xf bank_mask:0xf
	v_exp_f32_e32 v222, v200
	v_exp_f32_e32 v224, v230
	v_exp_f32_e32 v226, v232
	v_exp_f32_e32 v228, v234
	v_exp_f32_e32 v223, v201
	v_exp_f32_e32 v225, v231
	v_exp_f32_e32 v227, v233
	v_exp_f32_e32 v229, v235
	v_pk_fma_f32 v[222:223], v[222:223], v[168:169], v[168:169] op_sel:[0,1,1] op_sel_hi:[1,1,1]
	v_pk_fma_f32 v[224:225], v[224:225], v[176:177], v[176:177] op_sel:[0,1,1] op_sel_hi:[1,1,1]
	v_pk_fma_f32 v[226:227], v[226:227], v[190:191], v[190:191] op_sel:[0,1,1] op_sel_hi:[1,1,1]
	v_pk_fma_f32 v[228:229], v[228:229], v[198:199], v[198:199] op_sel:[0,1,1] op_sel_hi:[1,1,1]
	v_rcp_f32_e32 v222, v222
	v_rcp_f32_e32 v224, v224
	v_rcp_f32_e32 v226, v226
	v_rcp_f32_e32 v228, v228
	v_rcp_f32_e32 v223, v223
	v_rcp_f32_e32 v225, v225
	v_rcp_f32_e32 v227, v227
	v_rcp_f32_e32 v229, v229
	v_pk_mul_f32 v[222:223], v[200:201], v[222:223]
	v_pk_mul_f32 v[224:225], v[230:231], v[224:225]
	v_pk_mul_f32 v[226:227], v[232:233], v[226:227]
	v_pk_mul_f32 v[228:229], v[234:235], v[228:229]
	v_pk_mul_f32 v[192:193], v[44:45], v[248:249] op_sel:[0,0] op_sel_hi:[1,0]
	v_pk_mul_f32 v[44:45], v[222:223], v[44:45]
	v_pk_mul_f32 v[40:41], v[224:225], v[40:41]
	v_pk_mul_f32 v[36:37], v[226:227], v[36:37]
	v_pk_mul_f32 v[32:33], v[228:229], v[32:33]
	v_cndmask_b32_e64 v222, v50, 0, s[36:37]
	v_cndmask_b32_e64 v236, v50, 0, s[44:45]
	v_cndmask_b32_e64 v224, v62, v50, s[36:37]
	v_cndmask_b32_e64 v237, v62, v50, s[44:45]
	v_cndmask_b32_e64 v226, v58, v62, s[36:37]
	v_cndmask_b32_e64 v238, v58, v62, s[44:45]
	v_cndmask_b32_e64 v228, v54, v58, s[36:37]
	v_cndmask_b32_e64 v239, v54, v58, s[44:45]
	v_cndmask_b32_e64 v223, v51, 0, s[36:37]
	v_cndmask_b32_e64 v196, v51, 0, s[44:45]
	v_cndmask_b32_e64 v225, v63, v51, s[36:37]
	v_cndmask_b32_e64 v197, v63, v51, s[44:45]
	v_cndmask_b32_e64 v227, v59, v63, s[36:37]
	v_cndmask_b32_e64 v221, v59, v63, s[44:45]
	v_cndmask_b32_e64 v229, v55, v59, s[36:37]
	v_cndmask_b32_e64 v176, v55, v59, s[44:45]
	v_pk_fma_f32 v[202:203], v[94:95], v[50:51], v[86:87]
	v_pk_fma_f32 v[230:231], v[94:95], v[62:63], v[86:87]
	v_pk_fma_f32 v[232:233], v[94:95], v[58:59], v[86:87]
	v_pk_fma_f32 v[234:235], v[94:95], v[54:55], v[86:87]
	v_fmac_f32_dpp v202, v222, v90 row_ror:1 row_mask:0xf bank_mask:0xf
	v_fmac_f32_dpp v230, v224, v90 row_ror:1 row_mask:0xf bank_mask:0xf
	v_fmac_f32_dpp v232, v226, v90 row_ror:1 row_mask:0xf bank_mask:0xf
	v_fmac_f32_dpp v234, v228, v90 row_ror:1 row_mask:0xf bank_mask:0xf
	v_fmac_f32_dpp v203, v223, v91 row_ror:1 row_mask:0xf bank_mask:0xf
	v_fmac_f32_dpp v231, v225, v91 row_ror:1 row_mask:0xf bank_mask:0xf
	v_fmac_f32_dpp v233, v227, v91 row_ror:1 row_mask:0xf bank_mask:0xf
	v_fmac_f32_dpp v235, v229, v91 row_ror:1 row_mask:0xf bank_mask:0xf
	v_fmac_f32_dpp v202, v236, v82 row_ror:2 row_mask:0xf bank_mask:0xf
	v_fmac_f32_dpp v230, v237, v82 row_ror:2 row_mask:0xf bank_mask:0xf
	v_fmac_f32_dpp v232, v238, v82 row_ror:2 row_mask:0xf bank_mask:0xf
	v_fmac_f32_dpp v234, v239, v82 row_ror:2 row_mask:0xf bank_mask:0xf
	v_fmac_f32_dpp v203, v196, v83 row_ror:2 row_mask:0xf bank_mask:0xf
	v_fmac_f32_dpp v231, v197, v83 row_ror:2 row_mask:0xf bank_mask:0xf
	v_fmac_f32_dpp v233, v221, v83 row_ror:2 row_mask:0xf bank_mask:0xf
	v_fmac_f32_dpp v235, v176, v83 row_ror:2 row_mask:0xf bank_mask:0xf
	v_exp_f32_e32 v222, v202
	v_exp_f32_e32 v224, v230
	v_exp_f32_e32 v226, v232
	v_exp_f32_e32 v228, v234
	v_exp_f32_e32 v223, v203
	v_exp_f32_e32 v225, v231
	v_exp_f32_e32 v227, v233
	v_exp_f32_e32 v229, v235
	v_pk_fma_f32 v[222:223], v[222:223], v[168:169], v[168:169] op_sel:[0,1,1] op_sel_hi:[1,1,1]
	v_pk_fma_f32 v[224:225], v[224:225], v[176:177], v[176:177] op_sel:[0,1,1] op_sel_hi:[1,1,1]
	v_pk_fma_f32 v[226:227], v[226:227], v[190:191], v[190:191] op_sel:[0,1,1] op_sel_hi:[1,1,1]
	v_pk_fma_f32 v[228:229], v[228:229], v[198:199], v[198:199] op_sel:[0,1,1] op_sel_hi:[1,1,1]
	v_rcp_f32_e32 v222, v222
	v_rcp_f32_e32 v224, v224
	v_rcp_f32_e32 v226, v226
	v_rcp_f32_e32 v228, v228
	v_rcp_f32_e32 v223, v223
	v_rcp_f32_e32 v225, v225
	v_rcp_f32_e32 v227, v227
	v_rcp_f32_e32 v229, v229
	v_pk_mul_f32 v[222:223], v[202:203], v[222:223]
	v_pk_mul_f32 v[224:225], v[230:231], v[224:225]
	v_pk_mul_f32 v[226:227], v[232:233], v[226:227]
	v_pk_mul_f32 v[228:229], v[234:235], v[228:229]
	v_pk_mul_f32 v[194:195], v[46:47], v[248:249] op_sel:[0,0] op_sel_hi:[1,0]
	v_pk_mul_f32 v[46:47], v[222:223], v[46:47]
	v_pk_mul_f32 v[42:43], v[224:225], v[42:43]
	v_pk_mul_f32 v[38:39], v[226:227], v[38:39]
	v_pk_mul_f32 v[34:35], v[228:229], v[34:35]
	v_cndmask_b32_e64 v222, v20, 0, s[36:37]
	v_cndmask_b32_e64 v236, v20, 0, s[44:45]
	v_cndmask_b32_e64 v224, v28, v20, s[36:37]
	v_cndmask_b32_e64 v237, v28, v20, s[44:45]
	v_cndmask_b32_e64 v226, v16, v28, s[36:37]
	v_cndmask_b32_e64 v238, v16, v28, s[44:45]
	v_cndmask_b32_e64 v228, v24, v16, s[36:37]
	v_cndmask_b32_e64 v239, v24, v16, s[44:45]
	v_cndmask_b32_e64 v223, v21, 0, s[36:37]
	v_cndmask_b32_e64 v196, v21, 0, s[44:45]
	v_cndmask_b32_e64 v225, v29, v21, s[36:37]
	v_cndmask_b32_e64 v197, v29, v21, s[44:45]
	v_cndmask_b32_e64 v227, v17, v29, s[36:37]
	v_cndmask_b32_e64 v221, v17, v29, s[44:45]
	v_cndmask_b32_e64 v229, v25, v17, s[36:37]
	v_cndmask_b32_e64 v176, v25, v17, s[44:45]
	v_pk_fma_f32 v[204:205], v[76:77], v[20:21], v[68:69]
	v_pk_fma_f32 v[230:231], v[76:77], v[28:29], v[68:69]
	v_pk_fma_f32 v[232:233], v[76:77], v[16:17], v[68:69]
	v_pk_fma_f32 v[234:235], v[76:77], v[24:25], v[68:69]
	v_fmac_f32_dpp v204, v222, v72 row_ror:1 row_mask:0xf bank_mask:0xf
	v_fmac_f32_dpp v230, v224, v72 row_ror:1 row_mask:0xf bank_mask:0xf
	v_fmac_f32_dpp v232, v226, v72 row_ror:1 row_mask:0xf bank_mask:0xf
	v_fmac_f32_dpp v234, v228, v72 row_ror:1 row_mask:0xf bank_mask:0xf
	v_fmac_f32_dpp v205, v223, v73 row_ror:1 row_mask:0xf bank_mask:0xf
	v_fmac_f32_dpp v231, v225, v73 row_ror:1 row_mask:0xf bank_mask:0xf
	v_fmac_f32_dpp v233, v227, v73 row_ror:1 row_mask:0xf bank_mask:0xf
	v_fmac_f32_dpp v235, v229, v73 row_ror:1 row_mask:0xf bank_mask:0xf
	v_fmac_f32_dpp v204, v236, v64 row_ror:2 row_mask:0xf bank_mask:0xf
	v_fmac_f32_dpp v230, v237, v64 row_ror:2 row_mask:0xf bank_mask:0xf
	v_fmac_f32_dpp v232, v238, v64 row_ror:2 row_mask:0xf bank_mask:0xf
	v_fmac_f32_dpp v234, v239, v64 row_ror:2 row_mask:0xf bank_mask:0xf
	v_fmac_f32_dpp v205, v196, v65 row_ror:2 row_mask:0xf bank_mask:0xf
	v_fmac_f32_dpp v231, v197, v65 row_ror:2 row_mask:0xf bank_mask:0xf
	v_fmac_f32_dpp v233, v221, v65 row_ror:2 row_mask:0xf bank_mask:0xf
	v_fmac_f32_dpp v235, v176, v65 row_ror:2 row_mask:0xf bank_mask:0xf
	v_exp_f32_e32 v222, v204
	v_exp_f32_e32 v224, v230
	v_exp_f32_e32 v226, v232
	v_exp_f32_e32 v228, v234
	v_exp_f32_e32 v223, v205
	v_exp_f32_e32 v225, v231
	v_exp_f32_e32 v227, v233
	v_exp_f32_e32 v229, v235
	v_pk_fma_f32 v[222:223], v[222:223], v[168:169], v[168:169] op_sel:[0,1,1] op_sel_hi:[1,1,1]
	v_pk_fma_f32 v[224:225], v[224:225], v[176:177], v[176:177] op_sel:[0,1,1] op_sel_hi:[1,1,1]
	v_pk_fma_f32 v[226:227], v[226:227], v[190:191], v[190:191] op_sel:[0,1,1] op_sel_hi:[1,1,1]
	v_pk_fma_f32 v[228:229], v[228:229], v[198:199], v[198:199] op_sel:[0,1,1] op_sel_hi:[1,1,1]
	v_rcp_f32_e32 v222, v222
	v_rcp_f32_e32 v224, v224
	v_rcp_f32_e32 v226, v226
	v_rcp_f32_e32 v228, v228
	v_rcp_f32_e32 v223, v223
	v_rcp_f32_e32 v225, v225
	v_rcp_f32_e32 v227, v227
	v_rcp_f32_e32 v229, v229
	v_pk_mul_f32 v[222:223], v[204:205], v[222:223]
	v_pk_mul_f32 v[224:225], v[230:231], v[224:225]
	v_pk_mul_f32 v[226:227], v[232:233], v[226:227]
	v_pk_mul_f32 v[228:229], v[234:235], v[228:229]
	v_pk_mul_f32 v[240:241], v[12:13], v[248:249] op_sel:[0,0] op_sel_hi:[1,0]
	v_pk_mul_f32 v[12:13], v[222:223], v[12:13]
	v_pk_mul_f32 v[8:9], v[224:225], v[8:9]
	v_pk_mul_f32 v[4:5], v[226:227], v[4:5]
	v_pk_mul_f32 v[0:1], v[228:229], v[0:1]
	v_cndmask_b32_e64 v222, v22, 0, s[36:37]
	v_cndmask_b32_e64 v236, v22, 0, s[44:45]
	v_cndmask_b32_e64 v224, v30, v22, s[36:37]
	v_cndmask_b32_e64 v237, v30, v22, s[44:45]
	v_cndmask_b32_e64 v226, v18, v30, s[36:37]
	v_cndmask_b32_e64 v238, v18, v30, s[44:45]
	v_cndmask_b32_e64 v228, v26, v18, s[36:37]
	v_cndmask_b32_e64 v239, v26, v18, s[44:45]
	v_cndmask_b32_e64 v223, v23, 0, s[36:37]
	v_cndmask_b32_e64 v196, v23, 0, s[44:45]
	v_cndmask_b32_e64 v225, v31, v23, s[36:37]
	v_cndmask_b32_e64 v197, v31, v23, s[44:45]
	v_cndmask_b32_e64 v227, v19, v31, s[36:37]
	v_cndmask_b32_e64 v221, v19, v31, s[44:45]
	v_cndmask_b32_e64 v229, v27, v19, s[36:37]
	v_cndmask_b32_e64 v176, v27, v19, s[44:45]
	v_pk_fma_f32 v[206:207], v[78:79], v[22:23], v[70:71]
	v_pk_fma_f32 v[230:231], v[78:79], v[30:31], v[70:71]
	v_pk_fma_f32 v[232:233], v[78:79], v[18:19], v[70:71]
	v_pk_fma_f32 v[234:235], v[78:79], v[26:27], v[70:71]
	v_fmac_f32_dpp v206, v222, v74 row_ror:1 row_mask:0xf bank_mask:0xf
	v_fmac_f32_dpp v230, v224, v74 row_ror:1 row_mask:0xf bank_mask:0xf
	v_fmac_f32_dpp v232, v226, v74 row_ror:1 row_mask:0xf bank_mask:0xf
	v_fmac_f32_dpp v234, v228, v74 row_ror:1 row_mask:0xf bank_mask:0xf
	v_fmac_f32_dpp v207, v223, v75 row_ror:1 row_mask:0xf bank_mask:0xf
	v_fmac_f32_dpp v231, v225, v75 row_ror:1 row_mask:0xf bank_mask:0xf
	v_fmac_f32_dpp v233, v227, v75 row_ror:1 row_mask:0xf bank_mask:0xf
	v_fmac_f32_dpp v235, v229, v75 row_ror:1 row_mask:0xf bank_mask:0xf
	v_fmac_f32_dpp v206, v236, v66 row_ror:2 row_mask:0xf bank_mask:0xf
	v_fmac_f32_dpp v230, v237, v66 row_ror:2 row_mask:0xf bank_mask:0xf
	v_fmac_f32_dpp v232, v238, v66 row_ror:2 row_mask:0xf bank_mask:0xf
	v_fmac_f32_dpp v234, v239, v66 row_ror:2 row_mask:0xf bank_mask:0xf
	v_fmac_f32_dpp v207, v196, v67 row_ror:2 row_mask:0xf bank_mask:0xf
	v_fmac_f32_dpp v231, v197, v67 row_ror:2 row_mask:0xf bank_mask:0xf
	v_fmac_f32_dpp v233, v221, v67 row_ror:2 row_mask:0xf bank_mask:0xf
	v_fmac_f32_dpp v235, v176, v67 row_ror:2 row_mask:0xf bank_mask:0xf
	v_exp_f32_e32 v222, v206
	v_exp_f32_e32 v224, v230
	v_exp_f32_e32 v226, v232
	v_exp_f32_e32 v228, v234
	v_exp_f32_e32 v223, v207
	v_exp_f32_e32 v225, v231
	v_exp_f32_e32 v227, v233
	v_exp_f32_e32 v229, v235
	v_pk_fma_f32 v[222:223], v[222:223], v[168:169], v[168:169] op_sel:[0,1,1] op_sel_hi:[1,1,1]
	v_pk_fma_f32 v[224:225], v[224:225], v[176:177], v[176:177] op_sel:[0,1,1] op_sel_hi:[1,1,1]
	v_pk_fma_f32 v[226:227], v[226:227], v[190:191], v[190:191] op_sel:[0,1,1] op_sel_hi:[1,1,1]
	v_pk_fma_f32 v[228:229], v[228:229], v[198:199], v[198:199] op_sel:[0,1,1] op_sel_hi:[1,1,1]
	v_rcp_f32_e32 v222, v222
	v_rcp_f32_e32 v224, v224
	v_rcp_f32_e32 v226, v226
	v_rcp_f32_e32 v228, v228
	v_rcp_f32_e32 v223, v223
	v_rcp_f32_e32 v225, v225
	v_rcp_f32_e32 v227, v227
	v_rcp_f32_e32 v229, v229
	v_pk_mul_f32 v[222:223], v[206:207], v[222:223]
	v_pk_mul_f32 v[224:225], v[230:231], v[224:225]
	v_pk_mul_f32 v[226:227], v[232:233], v[226:227]
	v_pk_mul_f32 v[228:229], v[234:235], v[228:229]
	v_pk_mul_f32 v[242:243], v[14:15], v[248:249] op_sel:[0,0] op_sel_hi:[1,0]
	v_pk_mul_f32 v[14:15], v[222:223], v[14:15]
	v_pk_mul_f32 v[10:11], v[224:225], v[10:11]
	v_pk_mul_f32 v[6:7], v[226:227], v[6:7]
	v_pk_mul_f32 v[2:3], v[228:229], v[2:3]
	v_cvt_pk_bf16_f32 v44, v44, v45
	v_cvt_pk_bf16_f32 v45, v46, v47
	v_cvt_pk_bf16_f32 v46, v12, v13
	v_cvt_pk_bf16_f32 v47, v14, v15
	v_cvt_pk_bf16_f32 v40, v40, v41
	v_cvt_pk_bf16_f32 v41, v42, v43
	v_cvt_pk_bf16_f32 v42, v8, v9
	v_cvt_pk_bf16_f32 v43, v10, v11
	v_cvt_pk_bf16_f32 v36, v36, v37
	v_cvt_pk_bf16_f32 v37, v38, v39
	v_cvt_pk_bf16_f32 v38, v4, v5
	v_cvt_pk_bf16_f32 v39, v6, v7
	v_cvt_pk_bf16_f32 v32, v32, v33
	v_cvt_pk_bf16_f32 v33, v34, v35
	v_cvt_pk_bf16_f32 v34, v0, v1
	v_cvt_pk_bf16_f32 v35, v2, v3
	v_mul_f32_e32 v200, 0xbf317218, v200
	v_mul_f32_e32 v201, 0xbf317218, v201
	v_mul_f32_e32 v202, 0xbf317218, v202
	v_mul_f32_e32 v203, 0xbf317218, v203
	v_mul_f32_e32 v204, 0xbf317218, v204
	v_mul_f32_e32 v205, 0xbf317218, v205
	v_mul_f32_e32 v206, 0xbf317218, v206
	v_mul_f32_e32 v207, 0xbf317218, v207
	v_or_b32_e32 v170, s11, v216
	v_mul_u32_u24_e32 v170, s10, v170
	v_lshl_add_u32 v170, v170, 2, v190
	s_and_saveexec_b64 s[0:1], s[42:43]
	global_store_dwordx4 v170, v[200:203], s[50:51]
	global_store_dwordx4 v170, v[204:207], s[50:51] offset:16
	global_store_dwordx4 v170, v[192:195], s[92:93]
	global_store_dwordx4 v170, v[240:243], s[92:93] offset:16
	s_or_b64 exec, exec, s[0:1]
	v_add_u32_e32 v171, s11, v218
	v_mul_u32_u24_e32 v171, s10, v171
	v_lshl_add_u32 v171, v171, 2, v190
	s_and_saveexec_b64 s[0:1], s[44:45]
	global_store_dwordx4 v171, v[52:55], s[52:53]
	global_store_dwordx4 v171, v[24:27], s[52:53] offset:16
	s_or_b64 exec, exec, s[0:1]
	v_mad_u32_u24 v172, v168, s20, v189
	s_and_saveexec_b64 s[0:1], s[40:41]
	global_store_dwordx4 v172, v[44:47], s[94:95]
	s_or_b64 exec, exec, s[0:1]
	v_add_u32_e32 v172, 0x16000, v172
	global_store_dwordx4 v172, v[40:43], s[94:95]
	v_add_u32_e32 v172, 0x16000, v172
	global_store_dwordx4 v172, v[36:39], s[94:95]
	v_add_u32_e32 v172, 0x16000, v172
	global_store_dwordx4 v172, v[32:35], s[94:95]
	s_and_b64 vcc, exec, s[46:47]
	s_mov_b32 s0, s76
	s_mov_b32 s84, s78
	s_mov_b64 s[82:83], s[72:73]
	s_mov_b64 s[86:87], s[80:81]
	s_cbranch_vccnz .LBB0_146
	s_branch .LBB0_122
